# in-projection: half of the workgroups run their decode-row part before their six tiles, so the two halves' epilogue store bursts no longer coincide
# speedup vs baseline: 1.0371x; 1.0054x over previous
.LBB0_164:
	s_or_b64 exec, exec, s[0:1]
	v_mov_b32_e32 v8, v176
	s_cmpk_lt_i32 s54, 0x600
	s_waitcnt lgkmcnt(0)
	s_barrier
	s_mov_b32 s101, 0
	s_bitcmp1_b32 s54, 3
	s_cbranch_scc0 .Lin_big
	s_mov_b32 s101, 1
	v_readlane_b32 s64, v252, 6
	v_readlane_b32 s65, v252, 7
	s_add_u32 s64, s64, 0x20000
	s_addc_u32 s65, s65, 0
	s_branch .LBB0_294
.Lin_big:
	v_mov_b32_e32 v8, v176
	s_cmpk_lt_i32 s54, 0x600
	s_cselect_b64 s[0:1], -1, 0
	s_cmpk_gt_i32 s54, 0x5ff
	v_readfirstlane_b32 s2, v8
	s_cbranch_scc1 .LBB0_166
	s_ashr_i32 s3, s54, 31
	s_lshr_b32 s3, s3, 29
	s_add_i32 s3, s54, s3
	s_ashr_i32 s4, s3, 3
	s_and_b32 s3, s3, -8
	s_sub_i32 s3, s54, s3
	s_cmp_lt_i32 s3, 0
	s_movk_i32 s5, 0xc1
	s_cselect_b32 s5, s5, 0xc0
	s_mul_i32 s3, s5, s3
	s_add_i32 s3, s3, s4
	s_mul_hi_i32 s4, s3, 0x2aaaaaab
	s_lshr_b32 s5, s4, 31
	s_ashr_i32 s4, s4, 5
	s_add_i32 s4, s4, s5
	s_lshl_b32 s5, s4, 3
	s_mulk_i32 s4, 0xc0
	s_sub_i32 s3, s3, s4
	s_sext_i32_i16 s4, s3
	s_bfe_u32 s4, s4, 0x3001c
	s_add_i32 s4, s3, s4
	s_sext_i32_i16 s6, s4
	s_and_b32 s4, s4, 0xfff8
	s_sub_i32 s3, s3, s4
	s_sext_i32_i16 s3, s3
	s_add_i32 s8, s5, s3
	s_ashr_i32 s6, s6, 3

.LBB0_294:
	s_cmp_eq_u32 s101, 2
	s_cbranch_scc1 .Lin_seam2
	v_mov_b32_e32 v0, v176
	s_mul_i32 s2, s54, 3
	s_waitcnt vmcnt(0)
	s_barrier
	s_cmpk_gt_i32 s2, 0x5ff
	v_readfirstlane_b32 s0, v0
	s_cbranch_scc1 .LBB0_307
	v_lshrrev_b32_e32 v1, 1, v0
	v_and_b32_e32 v16, 24, v1
	v_and_b32_e32 v1, 63, v0
	s_ashr_i32 s3, s0, 6
	v_lshl_add_u32 v17, v1, 4, 0
	v_and_b32_e32 v6, 15, v0
	v_lshlrev_b32_e32 v1, 1, v0
	v_and_b32_e32 v0, 3, v0
	v_and_or_b32 v1, v1, 24, v0
	s_lshl_b32 s0, s3, 7
	s_lshl_b32 s8, s3, 11
	v_or_b32_e32 v0, s0, v16
	v_lshlrev_b32_e32 v2, 11, v1
	v_lshl_add_u32 v1, v1, 10, s0
	s_cmp_lt_i32 s3, 3
	v_readlane_b32 s16, v252, 0
	v_lshlrev_b32_e32 v0, 1, v0
	s_movk_i32 s1, 0x2000
	v_or_b32_e32 v1, v1, v16
	s_cselect_b64 s[4:5], -1, 0
	s_lshl_b32 s12, s3, 14
	v_readlane_b32 s22, v252, 6
	v_add3_u32 v0, v0, v2, s1
	v_lshlrev_b32_e32 v2, 1, v1
	v_lshl_add_u32 v1, v6, 10, s0
	v_readlane_b32 s23, v252, 7
	s_add_u32 s0, s22, 0x2120000
	s_addc_u32 s1, s23, 0
	s_add_u32 s14, s22, 0x5180000
	s_addc_u32 s15, s23, 0
	s_mul_i32 s6, s54, 48
	s_lshl_b32 s7, s3, 4
	v_or_b32_e32 v1, v1, v16
	v_mov_b32_e32 v7, 0
	v_readlane_b32 s17, v252, 1
	v_readlane_b32 s18, v252, 2
	v_readlane_b32 s19, v252, 3
	v_readlane_b32 s20, v252, 4
	v_readlane_b32 s21, v252, 5
	v_or_b32_e32 v18, 0x4000, v6
	s_add_i32 s16, s6, s7
	s_mul_i32 s6, s54, 12
	v_cndmask_b32_e64 v6, 0, 1, s[4:5]
	v_lshlrev_b32_e32 v4, 1, v1
	v_mov_b32_e32 v5, v7
	v_mov_b32_e32 v3, v7
	v_mov_b32_e32 v1, v7
	s_mul_i32 s13, s86, 3
	s_mul_i32 s17, s86, 48
	s_lshl_b32 s18, s3, 2
	s_add_i32 s19, s6, 8
	s_mul_i32 s20, s86, 12
	s_mul_i32 s21, s54, 0xc000
	s_mul_i32 s22, s86, 0xc000
	s_mov_b64 s[6:7], 0x2000000
	s_brev_b32 s23, 64
	v_add_u32_e32 v19, s8, v17
	v_cmp_ne_u32_e64 s[4:5], 1, v6
	s_movk_i32 s24, 0x3ff
	s_movk_i32 s25, 0xfa00
	s_mov_b32 s26, 0x1020000
	v_mov_b32_e32 v20, 0x3db504f3
	s_branch .LBB0_298

.LBB0_307:
	s_cmp_lg_u32 s101, 1
	s_cbranch_scc1 .Lin_seam2
	s_mov_b32 s101, 2
	s_branch .Lin_big

	.amdhsa_kernel _Z14fwd_megakernel3Ctx
		.amdhsa_group_segment_fixed_size 0
		.amdhsa_private_segment_fixed_size 0
		.amdhsa_kernarg_size 416
		.amdhsa_user_sgpr_count 2
		.amdhsa_user_sgpr_dispatch_ptr 0
		.amdhsa_user_sgpr_queue_ptr 0
		.amdhsa_user_sgpr_kernarg_segment_ptr 1
		.amdhsa_user_sgpr_dispatch_id 0
		.amdhsa_user_sgpr_kernarg_preload_length 0
		.amdhsa_user_sgpr_kernarg_preload_offset 0
		.amdhsa_user_sgpr_private_segment_size 0
		.amdhsa_uses_dynamic_stack 0
		.amdhsa_enable_private_segment 0
		.amdhsa_system_sgpr_workgroup_id_x 1
		.amdhsa_system_sgpr_workgroup_id_y 0
		.amdhsa_system_sgpr_workgroup_id_z 0
		.amdhsa_system_sgpr_workgroup_info 0
		.amdhsa_system_vgpr_workitem_id 2
		.amdhsa_next_free_vgpr 253
		.amdhsa_next_free_sgpr 102
		.amdhsa_accum_offset 256
		.amdhsa_reserve_vcc 1
		.amdhsa_float_round_mode_32 0
		.amdhsa_float_round_mode_16_64 0
		.amdhsa_float_denorm_mode_32 3
		.amdhsa_float_denorm_mode_16_64 3
		.amdhsa_dx10_clamp 1
		.amdhsa_ieee_mode 1
		.amdhsa_fp16_overflow 0
		.amdhsa_tg_split 0
		.amdhsa_exception_fp_ieee_invalid_op 0
		.amdhsa_exception_fp_denorm_src 0
		.amdhsa_exception_fp_ieee_div_zero 0
		.amdhsa_exception_fp_ieee_overflow 0
		.amdhsa_exception_fp_ieee_underflow 0
		.amdhsa_exception_fp_ieee_inexact 0
		.amdhsa_exception_int_div_zero 0
	.end_amdhsa_kernel

amdhsa.kernels:
  - .agpr_count:     0
    .args:
      - .offset:         0
        .size:           160
        .value_kind:     by_value
      - .offset:         160
        .size:           4
        .value_kind:     hidden_block_count_x
      - .offset:         164
        .size:           4
        .value_kind:     hidden_block_count_y
      - .offset:         168
        .size:           4
        .value_kind:     hidden_block_count_z
      - .offset:         172
        .size:           2
        .value_kind:     hidden_group_size_x
      - .offset:         174
        .size:           2
        .value_kind:     hidden_group_size_y
      - .offset:         176
        .size:           2
        .value_kind:     hidden_group_size_z
      - .offset:         178
        .size:           2
        .value_kind:     hidden_remainder_x
      - .offset:         180
        .size:           2
        .value_kind:     hidden_remainder_y
      - .offset:         182
        .size:           2
        .value_kind:     hidden_remainder_z
      - .offset:         200
        .size:           8
        .value_kind:     hidden_global_offset_x
      - .offset:         208
        .size:           8
        .value_kind:     hidden_global_offset_y
      - .offset:         216
        .size:           8
        .value_kind:     hidden_global_offset_z
      - .offset:         224
        .size:           2
        .value_kind:     hidden_grid_dims
      - .offset:         248
        .size:           8
        .value_kind:     hidden_multigrid_sync_arg
      - .offset:         280
        .size:           4
        .value_kind:     hidden_dynamic_lds_size
    .group_segment_fixed_size: 0
    .kernarg_segment_align: 8
    .kernarg_segment_size: 416
    .language:       OpenCL C
    .language_version:
      - 2
      - 0
    .max_flat_workgroup_size: 512
    .name:           _Z14fwd_megakernel3Ctx
    .private_segment_fixed_size: 0
    .sgpr_count:     108
    .sgpr_spill_count: 59
    .symbol:         _Z14fwd_megakernel3Ctx.kd
    .uniform_work_group_size: 1
    .uses_dynamic_stack: false
    .vgpr_count:     253
    .vgpr_spill_count: 0
    .wavefront_size: 64
